# prep: the cooperative-groups grid sync after the prep phase replaced by the kernel's own XCD-hierarchical barrier
# speedup vs baseline: 1.0589x; 1.0011x over previous
.LBB0_35:
	s_waitcnt lgkmcnt(0)
	s_barrier
	s_load_dword s0, s[94:95], 0xe0
	s_lshl_b32 s19, s2, 3
	s_lshl_b32 s56, s42, 3
	s_mul_i32 s81, s43, s42
	s_cmpk_lt_i32 s2, 0x810
	s_waitcnt lgkmcnt(0)
	s_mul_i32 s81, s81, s0
	s_cselect_b64 s[0:1], -1, 0
	s_ashr_i32 s3, s2, 31
	v_writelane_b32 v252, s0, 0
	s_ashr_i32 s43, s42, 31
	s_and_b32 s6, s42, 7
	v_writelane_b32 v252, s1, 1
	s_lshr_b32 s0, s3, 29
	s_add_i32 s0, s2, s0
	s_ashr_i32 s10, s0, 3
	s_and_b32 s0, s0, -8
	s_sub_i32 s11, s2, s0
	s_and_b32 s0, s2, 7
	s_ashr_i32 s1, s42, 3
	s_mul_i32 s0, s1, s0
	s_lshr_b32 s1, s2, 3
	s_add_i32 s7, s0, s1
	s_cmpk_lg_i32 s42, 0x100
	s_cselect_b64 s[0:1], -1, 0
	s_add_i32 s12, s42, 0x87f
	v_writelane_b32 v252, s0, 2
	s_cmpk_lt_i32 s2, 0x1080
	s_mov_b32 s73, 0
	v_writelane_b32 v252, s1, 3
	s_cselect_b64 s[0:1], -1, 0
	v_writelane_b32 v252, s0, 4
	s_lshr_b32 s13, s2, 7
	v_mov_b32_e32 v173, 0
	v_writelane_b32 v252, s1, 5
	s_and_b32 s0, s2, 0x7f
	s_and_b32 s1, s19, 0xffffe000
	s_lshl_b32 s4, s0, 6
	s_or_b32 s14, s1, s4
	s_cmp_lg_u32 s0, 0
	s_cselect_b64 s[0:1], -1, 0
	s_lshl_b32 s4, s2, 1
	s_and_b32 s4, s4, 0x7ffffff0
	s_add_i32 s15, s4, 0x6000
	s_cmpk_lt_i32 s2, 0xa0
	s_cselect_b64 s[4:5], -1, 0
	s_cmpk_lt_i32 s42, 0xc0
	v_writelane_b32 v252, s4, 6
	s_cselect_b64 s[8:9], -1, 0
	s_add_i32 s72, s2, 0xffffffe0
	v_writelane_b32 v252, s5, 7
	v_writelane_b32 v252, s8, 8
	s_or_b64 s[4:5], s[4:5], s[8:9]
	s_movk_i32 s33, 0xc0
	v_writelane_b32 v252, s9, 9
	v_writelane_b32 v252, s4, 10
	s_lshl_b64 s[8:9], s[72:73], 9
	s_mul_hi_i32 s85, s42, 0x16000
	v_writelane_b32 v252, s5, 11
	s_lshl_b64 s[4:5], s[2:3], 9
	v_writelane_b32 v252, s4, 12
	s_mul_i32 s84, s42, 0x16000
	s_movk_i32 s87, 0x4040
	v_writelane_b32 v252, s5, 13
	s_lshl_b64 s[4:5], s[42:43], 9
	v_writelane_b32 v252, s4, 14
	s_movk_i32 s92, 0x7fff
	s_movk_i32 s72, 0x300
	v_writelane_b32 v252, s5, 15
	s_add_i32 s4, s42, 0xffffffe0
	v_writelane_b32 v252, s8, 16
	s_mov_b32 s5, s73
	s_lshl_b64 s[4:5], s[4:5], 9
	v_writelane_b32 v252, s9, 17
	v_writelane_b32 v252, s4, 18
	s_cmpk_lt_i32 s2, 0x204
	v_mov_b32_e32 v216, 0x358637bd
	v_writelane_b32 v252, s5, 19
	s_cselect_b64 s[4:5], -1, 0
	v_writelane_b32 v252, s4, 20
	s_movk_i32 s86, 0x3000
	v_mov_b32_e32 v217, 0x1000
	v_writelane_b32 v252, s5, 21
	s_lshl_b32 s4, s11, 6
	s_or_b32 s4, s4, 4
	s_cmp_lt_i32 s11, 0
	s_movk_i32 s5, 0x103
	s_cselect_b32 s5, s5, 0x102
	s_mul_i32 s5, s11, s5
	s_add_i32 s5, s5, s10
	s_ashr_i32 s8, s5, 31
	s_lshr_b32 s8, s8, 25
	s_add_i32 s8, s5, s8
	s_ashr_i32 s9, s8, 7
	s_lshl_b32 s16, s9, 3
	s_sub_i32 s9, 0x81, s16
	s_and_b32 s8, s8, 0xffffff80
	s_min_u32 s17, s9, 8
	s_sub_i32 s18, s5, s8
	s_cmp_eq_u32 s6, 0
	s_cselect_b32 s6, s7, s2
	s_and_b32 s7, s6, 31
	s_cmp_lt_u32 s7, 16
	s_cselect_b64 s[8:9], -1, 0
	v_writelane_b32 v252, s8, 22
	s_lshr_b32 s8, s6, 5
	s_lshl_b32 s8, s8, 4
	s_add_i32 s8, s8, s7
	s_add_i32 s7, s8, 0x800
	v_cvt_f32_ubyte0_e32 v1, s17
	v_writelane_b32 v252, s9, 23
	v_writelane_b32 v252, s7, 24
	s_and_b32 s7, s6, 31
	v_writelane_b32 v252, s6, 25
	s_ashr_i32 s6, s6, 3
	s_and_b32 s6, s6, -4
	v_writelane_b32 v252, s6, 26
	s_xor_b32 s6, s7, 63
	v_writelane_b32 v252, s7, 27
	s_cmpk_lt_i32 s2, 0x1000
	v_writelane_b32 v252, s6, 28
	s_cselect_b64 s[6:7], -1, 0
	s_and_b64 s[8:9], s[6:7], exec
	s_cselect_b32 s8, 64, 16
	v_writelane_b32 v252, s8, 29
	s_cselect_b32 s8, s14, s15
	v_writelane_b32 v252, s8, 30
	s_cselect_b32 s8, s13, s2
	s_lshl_b32 s8, s8, 7
	s_and_b32 s8, s8, 0x380
	s_cmp_lt_i32 s11, 4
	s_mulk_i32 s11, 0x41
	s_cselect_b32 s4, s11, s4
	v_cvt_f32_i32_e32 v0, s18
	v_rcp_iflag_f32_e32 v2, v1
	s_add_i32 s4, s4, s10
	v_writelane_b32 v252, s8, 31
	s_ashr_i32 s8, s4, 31
	s_lshr_b32 s8, s8, 27
	s_add_i32 s8, s4, s8
	v_mul_f32_e32 v2, v0, v2
	s_ashr_i32 s9, s8, 5
	s_and_b64 s[0:1], s[0:1], s[6:7]
	v_trunc_f32_e32 v2, v2
	s_lshl_b32 s9, s9, 3
	v_writelane_b32 v252, s0, 32
	v_fma_f32 v0, -v2, v1, v0
	v_cvt_i32_f32_e32 v2, v2
	s_sub_i32 s10, 0x81, s9
	s_andn2_b32 s8, s8, 31
	v_writelane_b32 v252, s1, 33
	s_ashr_i32 s0, s18, 30
	s_min_u32 s10, s10, 8
	s_sub_i32 s4, s4, s8
	s_or_b32 s6, s0, 1
	v_cmp_ge_f32_e64 s[0:1], |v0|, v1
	s_and_b64 s[0:1], s[0:1], exec
	s_cselect_b32 s0, s6, 0
	v_readfirstlane_b32 s1, v2
	s_add_i32 s0, s1, s0
	s_abs_i32 s1, s42
	v_cvt_f32_u32_e32 v0, s1
	s_sub_i32 s7, 0, s1
	s_sext_i32_i8 s6, s0
	s_mul_i32 s0, s0, s17
	v_rcp_iflag_f32_e32 v0, v0
	v_writelane_b32 v252, s6, 34
	s_sub_i32 s0, s18, s0
	s_abs_i32 s6, s12
	v_mul_f32_e32 v0, 0x4f7ffffe, v0
	v_cvt_u32_f32_e32 v0, v0
	s_sext_i32_i8 s0, s0
	s_add_i32 s0, s16, s0
	v_writelane_b32 v252, s0, 35
	v_readfirstlane_b32 s8, v0
	s_mul_i32 s7, s7, s8
	s_mul_hi_u32 s7, s8, s7
	s_add_i32 s8, s8, s7
	s_mul_hi_u32 s7, s6, s8
	s_mul_i32 s8, s7, s1
	s_xor_b32 s0, s12, s42
	s_sub_i32 s6, s6, s8
	s_ashr_i32 s0, s0, 31
	s_add_i32 s8, s7, 1
	s_sub_i32 s11, s6, s1
	v_cvt_f32_ubyte0_e32 v1, s10
	s_cmp_ge_u32 s6, s1
	v_cvt_f32_i32_e32 v0, s4
	v_rcp_iflag_f32_e32 v2, v1
	s_cselect_b32 s7, s8, s7
	s_cselect_b32 s6, s11, s6
	s_add_i32 s8, s7, 1
	s_cmp_ge_u32 s6, s1
	s_cselect_b32 s1, s8, s7
	v_mul_f32_e32 v2, v0, v2
	s_xor_b32 s1, s1, s0
	v_trunc_f32_e32 v2, v2
	s_sub_i32 s0, s1, s0
	v_fma_f32 v0, -v2, v1, v0
	v_cvt_i32_f32_e32 v2, v2
	v_writelane_b32 v252, s0, 36
	s_ashr_i32 s0, s4, 30
	s_or_b32 s6, s0, 1
	v_cmp_ge_f32_e64 s[0:1], |v0|, v1
	s_and_b64 s[0:1], s[0:1], exec
	s_cselect_b32 s0, s6, 0
	v_readfirstlane_b32 s1, v2
	s_add_i32 s0, s1, s0
	s_sext_i32_i8 s1, s0
	v_writelane_b32 v252, s1, 37
	s_mul_i32 s1, s0, s10
	s_sub_i32 s1, s4, s1
	s_sext_i32_i8 s1, s1
	s_add_i32 s6, s9, s1
	s_movk_i32 s5, 0x80
	s_mov_b32 s4, s6
	s_ashr_i32 s7, s6, 31
	v_writelane_b32 v252, s4, 38
	s_lshl_b64 s[6:7], s[6:7], 19
	s_bfe_i64 s[0:1], s[0:1], 0x80000
	v_writelane_b32 v252, s5, 39
	v_writelane_b32 v252, s6, 40
	s_lshl_b64 s[0:1], s[0:1], 19
	s_ashr_i32 s57, s56, 31
	v_writelane_b32 v252, s7, 41
	v_writelane_b32 v252, s0, 42
	s_lshl_b64 s[60:61], s[56:57], 11
	v_mbcnt_lo_u32_b32 v0, -1, 0
	v_writelane_b32 v252, s1, 43
	s_lshl_b64 s[0:1], s[56:57], 12
	v_writelane_b32 v252, s0, 44
	v_mov_b32_e32 v218, 0x2000
	v_mov_b32_e32 v219, 0x2cfc000
	v_writelane_b32 v252, s1, 45
	v_writelane_b32 v252, s19, 46
	s_add_i32 s0, s19, s56
	v_writelane_b32 v252, s0, 47
	s_add_i32 s0, s2, s42
	s_lshl_b32 s1, s0, 3
	v_writelane_b32 v252, s1, 48
	s_lshl_b32 s0, s0, 1
	v_writelane_b32 v252, s0, 49
	s_lshl_b32 s0, s42, 1
	v_writelane_b32 v252, s0, 50
	s_lshl_b64 s[0:1], s[2:3], 2
	s_add_u32 s0, s0, 0x2cf5000
	s_addc_u32 s1, s1, 0
	v_writelane_b32 v252, s0, 51
	s_lshl_b64 s[6:7], s[42:43], 2
	v_mov_b32_e32 v220, 1
	v_writelane_b32 v252, s1, 52
	s_mul_hi_i32 s1, s2, 0x16000
	s_mul_i32 s0, s2, 0x16000
	v_writelane_b32 v252, s0, 53
	v_mov_b32_e32 v221, 0x3f4ccccd
	v_mbcnt_hi_u32_b32 v215, -1, v0
	v_writelane_b32 v252, s1, 54
	s_add_i32 s0, 0, 0x20000
	v_writelane_b32 v252, s0, 55
	s_add_i32 s0, 0, 0x20004
	v_writelane_b32 v252, s0, 56
	s_add_i32 s0, 0, 0x4400
	v_writelane_b32 v252, s0, 57
	s_add_i32 s0, 0, 0xd000
	v_writelane_b32 v252, s0, 58
	v_writelane_b32 v252, s6, 59
	v_mov_b64_e32 v[174:175], 0x80f
	v_mov_b64_e32 v[176:177], 0x810
	v_writelane_b32 v252, s7, 60
	s_lshl_b64 s[6:7], s[56:57], 13
	v_writelane_b32 v252, s6, 61
	v_mov_b32_e32 v222, 0xffffe003
	v_mov_b32_e32 v223, 0x7f800000
	v_writelane_b32 v252, s7, 62
	v_writelane_b32 v252, s94, 63
	v_mov_b32_e32 v224, 0xff800000
	v_mov_b32_e32 v225, 0x41b17218
	v_writelane_b32 v251, s95, 0
	v_mov_b32_e32 v226, 0x3fb8aa3b
	v_mov_b32_e32 v227, 0xffffff00
	v_mov_b32_e32 v228, 0xffffff80
	v_mov_b32_e32 v246, v173
	v_mov_b32_e32 v247, v173
	v_mov_b32_e32 v248, v173
	v_mov_b32_e32 v249, v173
	v_mov_b64_e32 v[178:179], 0x203
	v_mov_b64_e32 v[180:181], 0x204
	s_movk_i32 s4, 0x60
	s_add_i32 s1, 0, 0x11800
	s_add_i32 s0, 0, 0x17d00
	s_movk_i32 s69, 0xf0
	s_movk_i32 s93, 0x70
	s_mov_b64 s[76:77], 0
	s_mov_b64 s[78:79], 0x80
	s_mov_b32 s80, 0x3e38aa3b
	v_writelane_b32 v251, s96, 1
	s_nop 1
	v_writelane_b32 v251, s97, 2

.LBB0_1115_pb:
	global_load_dword v15, v173, s[12:13] sc1
	s_waitcnt lgkmcnt(0)
	global_load_dword v0, v173, s[14:15] sc1
	global_load_dword v1, v173, s[16:17] sc1
	global_load_dword v2, v173, s[18:19] sc1
	global_load_dword v3, v173, s[20:21] sc1
	global_load_dword v4, v173, s[22:23] sc1
	global_load_dword v5, v173, s[24:25] sc1
	global_load_dword v6, v173, s[26:27] sc1
	global_load_dword v7, v173, s[28:29] sc1
	global_load_dword v8, v173, s[30:31] sc1
	global_load_dword v9, v173, s[34:35] sc1
	global_load_dword v10, v173, s[36:37] sc1
	global_load_dword v11, v173, s[38:39] sc1
	global_load_dword v12, v173, s[40:41] sc1
	global_load_dword v13, v173, s[44:45] sc1
	global_load_dword v14, v173, s[46:47] sc1
	s_mov_b64 s[48:49], -1
	s_mov_b64 s[50:51], -1
	s_waitcnt vmcnt(14)
	v_add_u32_e32 v16, v0, v15
	s_waitcnt vmcnt(13)
	v_add_u32_e32 v16, v16, v1
	s_waitcnt vmcnt(12)
	v_add_u32_e32 v16, v16, v2
	s_waitcnt vmcnt(11)
	v_add_u32_e32 v16, v16, v3
	s_waitcnt vmcnt(10)
	v_add_u32_e32 v16, v16, v4
	s_waitcnt vmcnt(9)
	v_add_u32_e32 v16, v16, v5
	s_waitcnt vmcnt(8)
	v_add_u32_e32 v16, v16, v6
	s_waitcnt vmcnt(7)
	v_add_u32_e32 v16, v16, v7
	v_add_u32_e32 v16, v16, v8
	s_waitcnt vmcnt(5)
	v_add_u32_e32 v16, v16, v9
	s_waitcnt vmcnt(4)
	v_add_u32_e32 v16, v16, v10
	s_waitcnt vmcnt(3)
	v_add_u32_e32 v16, v16, v11
	s_waitcnt vmcnt(2)
	v_add_u32_e32 v16, v16, v12
	s_waitcnt vmcnt(1)
	v_add_u32_e32 v16, v16, v13
	s_waitcnt vmcnt(0)
	v_add_u32_e32 v16, v16, v14
	v_cmp_eq_u32_e32 vcc, s81, v16
	s_cbranch_vccnz .LBB0_1114_pb
	s_and_b32 s48, s55, 0xff
	s_cmp_eq_u32 s48, 0
	s_mov_b64 s[48:49], -1
	s_mov_b64 s[52:53], -1
	s_sleep 1
	s_cbranch_scc0 .LBB0_1119_pb
	global_load_dword v16, v173, s[10:11] sc1
	s_waitcnt vmcnt(0)
	v_cmp_eq_u32_e32 vcc, 0, v16
	s_cbranch_vccnz .LBB0_1121_pb
	s_mov_b64 s[52:53], 0

.LBB0_1163_pb:
	s_or_b64 exec, exec, s[6:7]
	s_mov_b64 s[8:9], s[94:95]
	s_waitcnt lgkmcnt(0)
	s_barrier
	s_branch .LBB0_48
